# mixA load balance 2: both FNet stage-1 items of a wave pair run on first-launched blocks (waves 0-1023), context NA items moved to blocks 0-255; FNet ctx items stay on waves 1536-2047
# speedup vs baseline: 1.0170x; 1.0170x over previous
.LBB0_572:
	v_readlane_b32 s0, v247, 7
	v_readlane_b32 s1, v247, 8
	s_lshl_b32 s40, s13, 1
	v_mov_b32_e32 v145, v137
	v_lshl_add_u64 v[34:35], v[152:153], 1, s[0:1]
	v_lshl_add_u64 v[34:35], v[34:35], 0, s[40:41]
	v_lshl_add_u64 v[50:51], v[34:35], 0, v[144:145]
	global_load_dwordx4 v[34:37], v[50:51], off
	global_load_dwordx4 v[38:41], v[50:51], off offset:32
	global_load_dwordx4 v[42:45], v[50:51], off offset:64
	global_load_dwordx4 v[46:49], v[50:51], off offset:96
	ds_bpermute_b32 v50, v196, v209
	v_readlane_b32 s50, v248, 57
	v_readlane_b32 s52, v248, 59
	s_sub_i32 s0, 0x3ff, s33
	s_cmpk_lt_i32 s33, 0x200
	s_cselect_b32 s33, s0, 0x7000
	v_readlane_b32 s51, v248, 58
	s_waitcnt lgkmcnt(0)
	v_add_f32_e32 v50, v209, v50
	v_div_scale_f32 v51, s[0:1], v50, v50, 1.0
	v_rcp_f32_e32 v52, v51
	v_div_scale_f32 v53, vcc, 1.0, v50, 1.0
	v_readlane_b32 s53, v248, 60
	v_fma_f32 v54, -v51, v52, 1.0
	v_fmac_f32_e32 v52, v54, v52
	v_mul_f32_e32 v54, v53, v52
	v_fma_f32 v55, -v51, v54, v53
	v_fmac_f32_e32 v54, v55, v52
	v_fma_f32 v51, -v51, v54, v53
	v_div_fmas_f32 v51, v51, v52, v54
	v_div_fixup_f32 v50, v51, v50, 1.0
	v_pk_mul_f32 v[18:19], v[18:19], v[50:51] op_sel_hi:[1,0]
	v_pk_mul_f32 v[20:21], v[20:21], v[50:51] op_sel_hi:[1,0]
	v_pk_mul_f32 v[22:23], v[22:23], v[50:51] op_sel_hi:[1,0]
	v_pk_mul_f32 v[24:25], v[24:25], v[50:51] op_sel_hi:[1,0]
	v_pk_mul_f32 v[26:27], v[26:27], v[50:51] op_sel_hi:[1,0]
	v_pk_mul_f32 v[28:29], v[28:29], v[50:51] op_sel_hi:[1,0]
	v_pk_mul_f32 v[30:31], v[30:31], v[50:51] op_sel_hi:[1,0]
	v_pk_mul_f32 v[32:33], v[32:33], v[50:51] op_sel_hi:[1,0]
	v_readlane_b32 s54, v248, 61
	s_cmpk_gt_i32 s33, 0x2ff
	v_readlane_b32 s55, v248, 62
	s_waitcnt vmcnt(3)
	v_mov_b32_e32 v51, v36
	v_mov_b32_e32 v52, v37
	s_nop 0
	v_permlane32_swap_b32_e32 v34, v51
	v_permlane32_swap_b32_e32 v35, v52
	s_waitcnt vmcnt(2)
	v_mov_b32_e32 v53, v40
	v_mov_b32_e32 v55, v41
	s_waitcnt vmcnt(1)
	v_mov_b32_e32 v56, v44
	v_mov_b32_e32 v57, v45
	v_lshlrev_b32_e32 v36, 16, v34
	v_and_b32_e32 v37, 0xffff0000, v34
	v_lshlrev_b32_e32 v34, 16, v35
	v_and_b32_e32 v35, 0xffff0000, v35
	v_lshlrev_b32_e32 v40, 16, v51
	v_and_b32_e32 v41, 0xffff0000, v51
	v_lshlrev_b32_e32 v44, 16, v52
	v_and_b32_e32 v45, 0xffff0000, v52
	v_permlane32_swap_b32_e32 v38, v53
	v_permlane32_swap_b32_e32 v39, v55
	v_pk_mul_f32 v[18:19], v[18:19], v[36:37]
	v_pk_mul_f32 v[20:21], v[20:21], v[34:35]
	v_pk_mul_f32 v[22:23], v[22:23], v[40:41]
	v_pk_mul_f32 v[24:25], v[24:25], v[44:45]
	s_waitcnt vmcnt(0)
	v_mov_b32_e32 v58, v48
	v_mov_b32_e32 v59, v49
	v_lshlrev_b32_e32 v48, 16, v38
	v_and_b32_e32 v49, 0xffff0000, v38
	v_lshlrev_b32_e32 v38, 16, v39
	v_and_b32_e32 v39, 0xffff0000, v39
	v_lshlrev_b32_e32 v52, 16, v53
	v_and_b32_e32 v53, 0xffff0000, v53
	v_lshlrev_b32_e32 v54, 16, v55
	v_and_b32_e32 v55, 0xffff0000, v55
	v_cvt_pk_bf16_f32 v18, v18, v19
	v_cvt_pk_bf16_f32 v19, v20, v21
	v_cvt_pk_bf16_f32 v20, v22, v23
	v_cvt_pk_bf16_f32 v21, v24, v25
	v_pk_mul_f32 v[26:27], v[26:27], v[48:49]
	v_pk_mul_f32 v[28:29], v[28:29], v[38:39]
	v_pk_mul_f32 v[30:31], v[30:31], v[52:53]
	v_pk_mul_f32 v[32:33], v[32:33], v[54:55]
	v_permlane32_swap_b32_e32 v18, v20
	v_permlane32_swap_b32_e32 v19, v21
	global_store_dwordx4 v[150:151], v[18:21], off
	v_permlane32_swap_b32_e32 v42, v56
	s_nop 0
	v_cvt_pk_bf16_f32 v18, v26, v27
	v_cvt_pk_bf16_f32 v19, v28, v29
	v_cvt_pk_bf16_f32 v20, v30, v31
	v_cvt_pk_bf16_f32 v21, v32, v33
	s_nop 0
	v_permlane32_swap_b32_e32 v18, v20
	v_permlane32_swap_b32_e32 v19, v21
	v_permlane32_swap_b32_e32 v43, v57
	global_store_dwordx4 v[150:151], v[18:21], off offset:32
	v_pk_mul_f32 v[2:3], v[2:3], v[50:51] op_sel_hi:[1,0]
	v_pk_mul_f32 v[4:5], v[4:5], v[50:51] op_sel_hi:[1,0]
	v_lshlrev_b32_e32 v18, 16, v42
	v_and_b32_e32 v19, 0xffff0000, v42
	v_pk_mul_f32 v[2:3], v[2:3], v[18:19]
	v_lshlrev_b32_e32 v18, 16, v43
	v_and_b32_e32 v19, 0xffff0000, v43
	v_pk_mul_f32 v[4:5], v[4:5], v[18:19]
	v_lshlrev_b32_e32 v18, 16, v56
	v_and_b32_e32 v19, 0xffff0000, v56
	v_pk_mul_f32 v[6:7], v[6:7], v[50:51] op_sel_hi:[1,0]
	v_pk_mul_f32 v[8:9], v[8:9], v[50:51] op_sel_hi:[1,0]
	v_pk_mul_f32 v[6:7], v[6:7], v[18:19]
	v_lshlrev_b32_e32 v18, 16, v57
	v_and_b32_e32 v19, 0xffff0000, v57
	v_pk_mul_f32 v[8:9], v[8:9], v[18:19]
	v_cvt_pk_bf16_f32 v2, v2, v3
	v_cvt_pk_bf16_f32 v3, v4, v5
	v_cvt_pk_bf16_f32 v4, v6, v7
	v_cvt_pk_bf16_f32 v5, v8, v9
	v_permlane32_swap_b32_e32 v46, v58
	v_permlane32_swap_b32_e32 v2, v4
	v_permlane32_swap_b32_e32 v3, v5
	v_permlane32_swap_b32_e32 v47, v59
	global_store_dwordx4 v[150:151], v[2:5], off offset:64
	v_pk_mul_f32 v[6:7], v[12:13], v[50:51] op_sel_hi:[1,0]
	v_pk_mul_f32 v[8:9], v[14:15], v[50:51] op_sel_hi:[1,0]
	v_lshlrev_b32_e32 v2, 16, v46
	v_and_b32_e32 v3, 0xffff0000, v46
	v_pk_mul_f32 v[4:5], v[10:11], v[50:51] op_sel_hi:[1,0]
	v_pk_mul_f32 v[10:11], v[16:17], v[50:51] op_sel_hi:[1,0]
	v_pk_mul_f32 v[2:3], v[4:5], v[2:3]
	v_lshlrev_b32_e32 v4, 16, v47
	v_and_b32_e32 v5, 0xffff0000, v47
	v_pk_mul_f32 v[4:5], v[6:7], v[4:5]
	v_lshlrev_b32_e32 v6, 16, v58
	v_and_b32_e32 v7, 0xffff0000, v58
	v_pk_mul_f32 v[6:7], v[8:9], v[6:7]
	v_lshlrev_b32_e32 v8, 16, v59
	v_and_b32_e32 v9, 0xffff0000, v59
	v_pk_mul_f32 v[8:9], v[10:11], v[8:9]
	v_cvt_pk_bf16_f32 v2, v2, v3
	v_cvt_pk_bf16_f32 v3, v4, v5
	v_cvt_pk_bf16_f32 v4, v6, v7
	v_cvt_pk_bf16_f32 v5, v8, v9
	s_nop 0
	v_permlane32_swap_b32_e32 v2, v4
	v_permlane32_swap_b32_e32 v3, v5
	global_store_dwordx4 v[150:151], v[2:5], off offset:96
	s_cbranch_scc1 .LBB0_667

.LBB0_667:
	v_readlane_b32 s0, v248, 0
	s_lshl_b32 s10, s0, 2
	v_lshrrev_b32_e32 v3, 6, v1
	v_add_u32_e32 v2, s10, v3
	s_lshl_b32 s13, s50, 2
	v_xad_u32 v2, v2, -1, s13
	v_add_u32_e32 v4, 0x800, v2
	v_cmp_gt_i32_e32 vcc, 0x200, v2
	v_cndmask_b32_e32 v2, v2, v4, vcc
	s_movk_i32 s0, 0x3ff
	v_cmp_lt_i32_e32 vcc, s0, v2
	s_and_saveexec_b64 s[0:1], vcc
	s_cbranch_execz .LBB0_674
	v_lshrrev_b32_e32 v4, 2, v1
	v_and_b32_e32 v5, 8, v4
	v_mov_b32_e32 v67, 0
	v_lshlrev_b32_e32 v70, 1, v5
	v_mov_b32_e32 v71, v67
	v_lshl_add_u64 v[8:9], s[82:83], 0, v[70:71]
	s_mov_b64 s[6:7], 0xe90c000
	v_lshlrev_b32_e32 v66, 8, v132
	v_lshl_add_u64 v[72:73], v[8:9], 0, s[6:7]
	s_mov_b64 s[6:7], 0xc900000
	v_lshl_add_u64 v[74:75], v[8:9], 0, s[6:7]
	v_lshl_add_u64 v[8:9], s[82:83], 0, v[66:67]
	v_lshlrev_b32_e32 v66, 4, v131
	v_lshl_add_u64 v[8:9], v[8:9], 0, v[66:67]
	s_mov_b64 s[6:7], 0xe900000
	v_lshl_add_u64 v[76:77], v[8:9], 0, s[6:7]
	s_mov_b64 s[6:7], 0xe902000
	v_lshl_add_u64 v[78:79], v[8:9], 0, s[6:7]
	s_mov_b64 s[6:7], 0xe904000
	v_lshl_add_u64 v[80:81], v[8:9], 0, s[6:7]
	s_mov_b64 s[6:7], 0xe906000
	v_lshl_add_u64 v[82:83], v[8:9], 0, s[6:7]
	s_mov_b64 s[6:7], 0xe902020
	v_lshl_add_u64 v[84:85], v[8:9], 0, s[6:7]
	s_mov_b64 s[6:7], 0xe904020
	v_lshl_add_u64 v[86:87], v[8:9], 0, s[6:7]
	s_mov_b64 s[6:7], 0xe906020
	v_lshl_add_u64 v[88:89], v[8:9], 0, s[6:7]
	s_mov_b64 s[6:7], 0xe902040
	v_lshl_add_u64 v[90:91], v[8:9], 0, s[6:7]
	s_mov_b64 s[6:7], 0xe904040
	v_lshl_add_u64 v[92:93], v[8:9], 0, s[6:7]
	s_mov_b64 s[6:7], 0xe906040
	v_lshl_add_u64 v[94:95], v[8:9], 0, s[6:7]
	s_mov_b64 s[6:7], 0xe902060
	v_lshl_add_u64 v[96:97], v[8:9], 0, s[6:7]
	s_mov_b64 s[6:7], 0xe904060
	v_lshl_add_u64 v[98:99], v[8:9], 0, s[6:7]
	s_mov_b64 s[6:7], 0xe906060
	v_lshl_add_u64 v[100:101], v[8:9], 0, s[6:7]
	s_mov_b64 s[6:7], 0xe902080
	v_lshl_add_u64 v[102:103], v[8:9], 0, s[6:7]
	s_mov_b64 s[6:7], 0xe904080
	v_lshl_add_u64 v[104:105], v[8:9], 0, s[6:7]
	s_mov_b64 s[6:7], 0xe906080
	v_lshl_add_u64 v[106:107], v[8:9], 0, s[6:7]
	s_mov_b64 s[6:7], 0xe9020a0
	v_lshl_add_u64 v[108:109], v[8:9], 0, s[6:7]
	s_mov_b64 s[6:7], 0xe9040a0
	v_lshl_add_u64 v[110:111], v[8:9], 0, s[6:7]
	s_mov_b64 s[6:7], 0xe9060a0
	v_lshl_add_u64 v[112:113], v[8:9], 0, s[6:7]
	s_mov_b64 s[6:7], 0xe9020c0
	v_lshl_add_u64 v[114:115], v[8:9], 0, s[6:7]
	s_mov_b64 s[6:7], 0xe9040c0
	s_add_u32 s2, s82, 0x3000000
	v_lshl_add_u64 v[116:117], v[8:9], 0, s[6:7]
	s_mov_b64 s[6:7], 0xe9060c0
	s_addc_u32 s3, s83, 0
	v_lshl_add_u64 v[118:119], v[8:9], 0, s[6:7]
	s_mov_b64 s[6:7], 0xe9020e0
	s_add_u32 s4, s82, 0x3c00000
	v_lshl_add_u64 v[120:121], v[8:9], 0, s[6:7]
	s_mov_b64 s[6:7], 0xe9040e0
	s_addc_u32 s5, s83, 0
	v_lshl_add_u64 v[122:123], v[8:9], 0, s[6:7]
	s_mov_b64 s[6:7], 0xe9060e0
	v_lshl_add_u64 v[124:125], v[8:9], 0, s[6:7]
	s_add_u32 s6, s82, 0xe94c000
	v_or_b32_e32 v149, 32, v132
	s_addc_u32 s7, s83, 0
	v_sub_u32_e32 v3, s13, v3
	v_lshlrev_b32_e32 v4, 6, v132
	v_lshlrev_b32_e32 v6, 6, v149
	s_add_u32 s8, s82, 0xd500000
	v_subrev_u32_e32 v3, s10, v3
	v_or_b32_e32 v68, 0x200000, v134
	v_mov_b32_e32 v69, v67
	v_lshlrev_b32_e32 v148, 8, v131
	s_addc_u32 s9, s83, 0
	v_add_u32_e32 v71, 0xfffff800, v2
	v_lshlrev_b32_e32 v150, 4, v2
	s_lshl_b32 s16, s50, 6
	v_lshlrev_b32_e32 v151, 7, v2
	s_lshl_b32 s17, s50, 9
	s_mov_b64 s[10:11], 0
	s_movk_i32 s18, 0x7ff
	s_movk_i32 s19, 0x80
	s_mov_b32 s20, 0x8000
	s_mov_b32 s21, 0x10000
	s_mov_b32 s22, 0x18000
	s_mov_b32 s12, 0x3bb504f3
	s_movk_i32 s23, 0x1ff
	v_lshlrev_b32_e32 v126, 1, v134
	v_lshlrev_b32_e32 v128, 1, v4
	v_lshlrev_b32_e32 v136, 1, v6
	s_movk_i32 s24, 0x9ff
	s_branch .LBB0_670
.LBB0_669:
	s_or_b64 exec, exec, s[14:15]
	v_add_u32_e32 v2, 0xfffffc00, v71
	v_cmp_gt_i32_e32 vcc, 0xfffffc00, v71
	v_mov_b32_e32 v66, 0x7000
	v_cndmask_b32_e32 v2, v2, v66, vcc
	v_cmp_lt_i32_e32 vcc, -1, v71
	v_cndmask_b32_e32 v71, v2, v66, vcc
	v_add_u32_e32 v2, 0x800, v71
	v_cmp_lt_i32_e32 vcc, s24, v2
	v_lshlrev_b32_e32 v150, 4, v2
	s_or_b64 s[10:11], vcc, s[10:11]
	v_lshlrev_b32_e32 v151, 7, v2
	s_andn2_b64 exec, exec, s[10:11]
	s_cbranch_execz .LBB0_674

.LBB0_1464:
	v_readlane_b32 s0, v247, 2
	v_readlane_b32 s1, v247, 3
	s_lshl_b32 s40, s42, 1
	v_mov_b32_e32 v147, v139
	v_lshl_add_u64 v[34:35], v[154:155], 1, s[0:1]
	v_lshl_add_u64 v[34:35], v[34:35], 0, s[40:41]
	v_lshl_add_u64 v[46:47], v[34:35], 0, v[146:147]
	global_load_dwordx4 v[34:37], v[46:47], off
	global_load_dwordx4 v[38:41], v[46:47], off offset:32
	global_load_dwordx4 v[42:45], v[46:47], off offset:64
	s_nop 0
	global_load_dwordx4 v[46:49], v[46:47], off offset:96
	ds_bpermute_b32 v50, v198, v211
	v_readlane_b32 s50, v248, 57
	v_readlane_b32 s52, v248, 59
	s_sub_i32 s0, 0x3ff, s33
	s_cmpk_lt_i32 s33, 0x200
	s_cselect_b32 s33, s0, 0x7000
	v_readlane_b32 s51, v248, 58
	s_waitcnt lgkmcnt(0)
	v_add_f32_e32 v50, v211, v50
	v_div_scale_f32 v51, s[0:1], v50, v50, 1.0
	v_rcp_f32_e32 v52, v51
	v_div_scale_f32 v53, vcc, 1.0, v50, 1.0
	v_readlane_b32 s53, v248, 60
	v_fma_f32 v54, -v51, v52, 1.0
	v_fmac_f32_e32 v52, v54, v52
	v_mul_f32_e32 v54, v53, v52
	v_fma_f32 v55, -v51, v54, v53
	v_fmac_f32_e32 v54, v55, v52
	v_fma_f32 v51, -v51, v54, v53
	v_div_fmas_f32 v51, v51, v52, v54
	v_div_fixup_f32 v50, v51, v50, 1.0
	v_pk_mul_f32 v[18:19], v[18:19], v[50:51] op_sel_hi:[1,0]
	v_pk_mul_f32 v[20:21], v[20:21], v[50:51] op_sel_hi:[1,0]
	v_pk_mul_f32 v[22:23], v[22:23], v[50:51] op_sel_hi:[1,0]
	v_pk_mul_f32 v[24:25], v[24:25], v[50:51] op_sel_hi:[1,0]
	v_pk_mul_f32 v[26:27], v[26:27], v[50:51] op_sel_hi:[1,0]
	v_pk_mul_f32 v[28:29], v[28:29], v[50:51] op_sel_hi:[1,0]
	v_pk_mul_f32 v[30:31], v[30:31], v[50:51] op_sel_hi:[1,0]
	v_pk_mul_f32 v[32:33], v[32:33], v[50:51] op_sel_hi:[1,0]
	v_readlane_b32 s54, v248, 61
	s_cmpk_gt_i32 s33, 0x2ff
	v_readlane_b32 s55, v248, 62
	s_waitcnt vmcnt(3)
	v_mov_b32_e32 v51, v36
	v_mov_b32_e32 v52, v37
	s_nop 0
	v_permlane32_swap_b32_e32 v34, v51
	v_permlane32_swap_b32_e32 v35, v52
	s_waitcnt vmcnt(2)
	v_mov_b32_e32 v53, v40
	v_mov_b32_e32 v55, v41
	s_waitcnt vmcnt(1)
	v_mov_b32_e32 v56, v44
	v_mov_b32_e32 v57, v45
	v_lshlrev_b32_e32 v36, 16, v34
	v_and_b32_e32 v37, 0xffff0000, v34
	v_lshlrev_b32_e32 v34, 16, v35
	v_and_b32_e32 v35, 0xffff0000, v35
	v_lshlrev_b32_e32 v40, 16, v51
	v_and_b32_e32 v41, 0xffff0000, v51
	v_lshlrev_b32_e32 v44, 16, v52
	v_and_b32_e32 v45, 0xffff0000, v52
	v_permlane32_swap_b32_e32 v38, v53
	v_permlane32_swap_b32_e32 v39, v55
	v_pk_mul_f32 v[18:19], v[18:19], v[36:37]
	v_pk_mul_f32 v[20:21], v[20:21], v[34:35]
	v_pk_mul_f32 v[22:23], v[22:23], v[40:41]
	v_pk_mul_f32 v[24:25], v[24:25], v[44:45]
	s_waitcnt vmcnt(0)
	v_mov_b32_e32 v58, v48
	v_mov_b32_e32 v59, v49
	v_lshlrev_b32_e32 v48, 16, v38
	v_and_b32_e32 v49, 0xffff0000, v38
	v_lshlrev_b32_e32 v38, 16, v39
	v_and_b32_e32 v39, 0xffff0000, v39
	v_lshlrev_b32_e32 v52, 16, v53
	v_and_b32_e32 v53, 0xffff0000, v53
	v_lshlrev_b32_e32 v54, 16, v55
	v_and_b32_e32 v55, 0xffff0000, v55
	v_cvt_pk_bf16_f32 v18, v18, v19
	v_cvt_pk_bf16_f32 v19, v20, v21
	v_cvt_pk_bf16_f32 v20, v22, v23
	v_cvt_pk_bf16_f32 v21, v24, v25
	v_pk_mul_f32 v[26:27], v[26:27], v[48:49]
	v_pk_mul_f32 v[28:29], v[28:29], v[38:39]
	v_pk_mul_f32 v[30:31], v[30:31], v[52:53]
	v_pk_mul_f32 v[32:33], v[32:33], v[54:55]
	v_permlane32_swap_b32_e32 v18, v20
	v_permlane32_swap_b32_e32 v19, v21
	global_store_dwordx4 v[152:153], v[18:21], off
	v_permlane32_swap_b32_e32 v42, v56
	s_nop 0
	v_cvt_pk_bf16_f32 v18, v26, v27
	v_cvt_pk_bf16_f32 v19, v28, v29
	v_cvt_pk_bf16_f32 v20, v30, v31
	v_cvt_pk_bf16_f32 v21, v32, v33
	s_nop 0
	v_permlane32_swap_b32_e32 v18, v20
	v_permlane32_swap_b32_e32 v19, v21
	v_permlane32_swap_b32_e32 v43, v57
	global_store_dwordx4 v[152:153], v[18:21], off offset:32
	v_pk_mul_f32 v[2:3], v[2:3], v[50:51] op_sel_hi:[1,0]
	v_pk_mul_f32 v[4:5], v[4:5], v[50:51] op_sel_hi:[1,0]
	v_lshlrev_b32_e32 v18, 16, v42
	v_and_b32_e32 v19, 0xffff0000, v42
	v_pk_mul_f32 v[2:3], v[2:3], v[18:19]
	v_lshlrev_b32_e32 v18, 16, v43
	v_and_b32_e32 v19, 0xffff0000, v43
	v_pk_mul_f32 v[4:5], v[4:5], v[18:19]
	v_lshlrev_b32_e32 v18, 16, v56
	v_and_b32_e32 v19, 0xffff0000, v56
	v_pk_mul_f32 v[6:7], v[6:7], v[50:51] op_sel_hi:[1,0]
	v_pk_mul_f32 v[8:9], v[8:9], v[50:51] op_sel_hi:[1,0]
	v_pk_mul_f32 v[6:7], v[6:7], v[18:19]
	v_lshlrev_b32_e32 v18, 16, v57
	v_and_b32_e32 v19, 0xffff0000, v57
	v_pk_mul_f32 v[8:9], v[8:9], v[18:19]
	v_cvt_pk_bf16_f32 v2, v2, v3
	v_cvt_pk_bf16_f32 v3, v4, v5
	v_cvt_pk_bf16_f32 v4, v6, v7
	v_cvt_pk_bf16_f32 v5, v8, v9
	v_permlane32_swap_b32_e32 v46, v58
	v_permlane32_swap_b32_e32 v2, v4
	v_permlane32_swap_b32_e32 v3, v5
	v_permlane32_swap_b32_e32 v47, v59
	global_store_dwordx4 v[152:153], v[2:5], off offset:64
	v_pk_mul_f32 v[6:7], v[12:13], v[50:51] op_sel_hi:[1,0]
	v_pk_mul_f32 v[8:9], v[14:15], v[50:51] op_sel_hi:[1,0]
	v_lshlrev_b32_e32 v2, 16, v46
	v_and_b32_e32 v3, 0xffff0000, v46
	v_pk_mul_f32 v[4:5], v[10:11], v[50:51] op_sel_hi:[1,0]
	v_pk_mul_f32 v[10:11], v[16:17], v[50:51] op_sel_hi:[1,0]
	v_pk_mul_f32 v[2:3], v[4:5], v[2:3]
	v_lshlrev_b32_e32 v4, 16, v47
	v_and_b32_e32 v5, 0xffff0000, v47
	v_pk_mul_f32 v[4:5], v[6:7], v[4:5]
	v_lshlrev_b32_e32 v6, 16, v58
	v_and_b32_e32 v7, 0xffff0000, v58
	v_pk_mul_f32 v[6:7], v[8:9], v[6:7]
	v_lshlrev_b32_e32 v8, 16, v59
	v_and_b32_e32 v9, 0xffff0000, v59
	v_pk_mul_f32 v[8:9], v[10:11], v[8:9]
	v_cvt_pk_bf16_f32 v2, v2, v3
	v_cvt_pk_bf16_f32 v3, v4, v5
	v_cvt_pk_bf16_f32 v4, v6, v7
	v_cvt_pk_bf16_f32 v5, v8, v9
	s_nop 0
	v_permlane32_swap_b32_e32 v2, v4
	v_permlane32_swap_b32_e32 v3, v5
	global_store_dwordx4 v[152:153], v[2:5], off offset:96
	s_cbranch_scc1 .LBB0_1559

.LBB0_1559:
	v_readlane_b32 s0, v248, 0
	s_lshl_b32 s10, s0, 2
	v_add_u32_e32 v2, s10, v186
	s_lshl_b32 s13, s50, 2
	v_xad_u32 v2, v2, -1, s13
	v_add_u32_e32 v4, 0x800, v2
	v_cmp_gt_i32_e32 vcc, 0x200, v2
	v_cndmask_b32_e32 v2, v2, v4, vcc
	s_movk_i32 s0, 0x3ff
	v_cmp_lt_i32_e32 vcc, s0, v2
	s_and_saveexec_b64 s[0:1], vcc
	s_cbranch_execz .LBB0_1566
	v_and_b32_e32 v3, 8, v187
	v_mov_b32_e32 v67, 0
	v_lshlrev_b32_e32 v70, 1, v3
	v_mov_b32_e32 v71, v67
	v_lshl_add_u64 v[8:9], s[82:83], 0, v[70:71]
	s_mov_b64 s[6:7], 0xe90c000
	v_lshlrev_b32_e32 v66, 8, v132
	v_lshl_add_u64 v[72:73], v[8:9], 0, s[6:7]
	s_mov_b64 s[6:7], 0xc900000
	v_lshl_add_u64 v[74:75], v[8:9], 0, s[6:7]
	v_lshl_add_u64 v[8:9], s[82:83], 0, v[66:67]
	v_mov_b32_e32 v137, v67
	v_lshl_add_u64 v[8:9], v[8:9], 0, v[136:137]
	s_mov_b64 s[6:7], 0xe900000
	v_lshl_add_u64 v[76:77], v[8:9], 0, s[6:7]
	s_mov_b64 s[6:7], 0xe902000
	v_lshl_add_u64 v[78:79], v[8:9], 0, s[6:7]
	s_mov_b64 s[6:7], 0xe904000
	v_lshl_add_u64 v[80:81], v[8:9], 0, s[6:7]
	s_mov_b64 s[6:7], 0xe906000
	v_lshl_add_u64 v[82:83], v[8:9], 0, s[6:7]
	s_mov_b64 s[6:7], 0xe902020
	v_lshl_add_u64 v[84:85], v[8:9], 0, s[6:7]
	s_mov_b64 s[6:7], 0xe904020
	v_lshl_add_u64 v[86:87], v[8:9], 0, s[6:7]
	s_mov_b64 s[6:7], 0xe906020
	v_lshl_add_u64 v[88:89], v[8:9], 0, s[6:7]
	s_mov_b64 s[6:7], 0xe902040
	v_lshl_add_u64 v[90:91], v[8:9], 0, s[6:7]
	s_mov_b64 s[6:7], 0xe904040
	v_lshl_add_u64 v[92:93], v[8:9], 0, s[6:7]
	s_mov_b64 s[6:7], 0xe906040
	v_lshl_add_u64 v[94:95], v[8:9], 0, s[6:7]
	s_mov_b64 s[6:7], 0xe902060
	v_lshl_add_u64 v[96:97], v[8:9], 0, s[6:7]
	s_mov_b64 s[6:7], 0xe904060
	v_lshl_add_u64 v[98:99], v[8:9], 0, s[6:7]
	s_mov_b64 s[6:7], 0xe906060
	v_lshl_add_u64 v[100:101], v[8:9], 0, s[6:7]
	s_mov_b64 s[6:7], 0xe902080
	v_lshl_add_u64 v[102:103], v[8:9], 0, s[6:7]
	s_mov_b64 s[6:7], 0xe904080
	v_lshl_add_u64 v[104:105], v[8:9], 0, s[6:7]
	s_mov_b64 s[6:7], 0xe906080
	v_lshl_add_u64 v[106:107], v[8:9], 0, s[6:7]
	s_mov_b64 s[6:7], 0xe9020a0
	v_lshl_add_u64 v[108:109], v[8:9], 0, s[6:7]
	s_mov_b64 s[6:7], 0xe9040a0
	v_lshl_add_u64 v[110:111], v[8:9], 0, s[6:7]
	s_mov_b64 s[6:7], 0xe9060a0
	v_lshl_add_u64 v[112:113], v[8:9], 0, s[6:7]
	s_mov_b64 s[6:7], 0xe9020c0
	v_lshl_add_u64 v[114:115], v[8:9], 0, s[6:7]
	s_mov_b64 s[6:7], 0xe9040c0
	s_add_u32 s2, s82, 0x3000000
	v_lshl_add_u64 v[116:117], v[8:9], 0, s[6:7]
	s_mov_b64 s[6:7], 0xe9060c0
	s_addc_u32 s3, s83, 0
	v_lshl_add_u64 v[118:119], v[8:9], 0, s[6:7]
	s_mov_b64 s[6:7], 0xe9020e0
	s_add_u32 s4, s82, 0x3c00000
	v_lshl_add_u64 v[120:121], v[8:9], 0, s[6:7]
	s_mov_b64 s[6:7], 0xe9040e0
	s_addc_u32 s5, s83, 0
	v_lshl_add_u64 v[122:123], v[8:9], 0, s[6:7]
	s_mov_b64 s[6:7], 0xe9060e0
	v_lshl_add_u64 v[124:125], v[8:9], 0, s[6:7]
	s_add_u32 s6, s82, 0xe94c000
	v_or_b32_e32 v133, 32, v132
	s_addc_u32 s7, s83, 0
	v_sub_u32_e32 v3, s13, v186
	v_lshlrev_b32_e32 v4, 6, v132
	v_lshlrev_b32_e32 v6, 6, v133
	s_add_u32 s8, s82, 0xd500000
	v_subrev_u32_e32 v3, s10, v3
	v_or_b32_e32 v68, 0x200000, v134
	v_mov_b32_e32 v69, v67
	v_lshlrev_b32_e32 v131, 8, v131
	s_addc_u32 s9, s83, 0
	v_add_u32_e32 v71, 0xfffff800, v2
	v_lshlrev_b32_e32 v146, 4, v2
	s_lshl_b32 s16, s50, 6
	v_lshlrev_b32_e32 v147, 7, v2
	s_lshl_b32 s17, s50, 9
	s_mov_b64 s[10:11], 0
	s_movk_i32 s18, 0x7ff
	s_movk_i32 s19, 0x80
	s_mov_b32 s20, 0x8000
	s_mov_b32 s21, 0x10000
	s_mov_b32 s22, 0x18000
	s_mov_b32 s12, 0x3bb504f3
	s_movk_i32 s23, 0x1ff
	v_lshlrev_b32_e32 v126, 1, v134
	v_lshlrev_b32_e32 v128, 1, v4
	v_lshlrev_b32_e32 v134, 1, v6
	s_movk_i32 s24, 0x9ff
	s_branch .LBB0_1562
.LBB0_1561:
	s_or_b64 exec, exec, s[14:15]
	v_add_u32_e32 v2, 0xfffffc00, v71
	v_cmp_gt_i32_e32 vcc, 0xfffffc00, v71
	v_mov_b32_e32 v66, 0x7000
	v_cndmask_b32_e32 v2, v2, v66, vcc
	v_cmp_lt_i32_e32 vcc, -1, v71
	v_cndmask_b32_e32 v71, v2, v66, vcc
	v_add_u32_e32 v2, 0x800, v71
	v_cmp_lt_i32_e32 vcc, s24, v2
	v_lshlrev_b32_e32 v146, 4, v2
	s_or_b64 s[10:11], vcc, s[10:11]
	v_lshlrev_b32_e32 v147, 7, v2
	s_andn2_b64 exec, exec, s[10:11]
	s_cbranch_execz .LBB0_1566
